# prompt LayerNorm/transposition + spatial-gate units: the four column groups of a chunk mapped to workgroups of the same XCD (shared L2 reads)
# speedup vs baseline: 1.0049x; 1.0049x over previous
.LBB0_343:
	s_and_b32 s99, s2, 7
	s_lshr_b32 s98, s2, 5
	s_lshl_b32 s98, s98, 3
	s_add_i32 s99, s99, s98
	s_lshl_b32 s99, s99, 2
	s_bfe_u32 s98, s2, 0x20003
	s_add_i32 s99, s99, s98
	s_cmpk_lg_i32 s26, 0x100
	s_cselect_b32 s99, s2, s99
	s_add_u32 s40, s34, 0x16200000
	s_addc_u32 s41, s35, 0
	s_cmpk_lt_i32 s2, 0x100
	s_cselect_b64 s[42:43], -1, 0
	s_cmpk_gt_i32 s2, 0xff
	s_cbranch_scc1 .LBB0_352
	v_mbcnt_hi_u32_b32 v0, -1, v165
	v_and_b32_e32 v1, 64, v0
	v_add_u32_e32 v1, 64, v1
	v_xor_b32_e32 v2, 1, v0
	v_cmp_lt_i32_e32 vcc, v2, v1
	s_ashr_i32 s9, s8, 31
	s_lshl_b64 s[4:5], s[8:9], 3
	v_cndmask_b32_e32 v2, v0, v2, vcc
	v_lshlrev_b32_e32 v98, 2, v2
	v_xor_b32_e32 v2, 2, v0
	v_cmp_lt_i32_e32 vcc, v2, v1
	s_add_u32 s4, s0, s4
	s_addc_u32 s5, s1, s5
	v_cndmask_b32_e32 v2, v0, v2, vcc
	v_lshlrev_b32_e32 v99, 2, v2
	v_xor_b32_e32 v2, 4, v0
	v_cmp_lt_i32_e32 vcc, v2, v1
	s_ashr_i32 s7, s6, 31
	s_lshl_b64 s[6:7], s[6:7], 3
	v_cndmask_b32_e32 v2, v0, v2, vcc
	v_lshlrev_b32_e32 v100, 2, v2
	v_xor_b32_e32 v2, 8, v0
	v_cmp_lt_i32_e32 vcc, v2, v1
	s_add_u32 s6, s0, s6
	s_addc_u32 s7, s1, s7
	v_cndmask_b32_e32 v2, v0, v2, vcc
	v_lshlrev_b32_e32 v101, 2, v2
	v_xor_b32_e32 v2, 16, v0
	v_cmp_lt_i32_e32 vcc, v2, v1
	s_load_dwordx2 s[44:45], s[4:5], 0x0
	s_load_dwordx2 s[46:47], s[6:7], 0x0
	v_cndmask_b32_e32 v2, v0, v2, vcc
	v_lshlrev_b32_e32 v102, 2, v2
	v_xor_b32_e32 v2, 32, v0
	v_cmp_lt_i32_e32 vcc, v2, v1
	s_movk_i32 s4, 0x210
	v_mov_b32_e32 v1, 0
	v_cndmask_b32_e32 v0, v0, v2, vcc
	v_lshlrev_b32_e32 v103, 2, v0
	v_and_b32_e32 v0, 0x78, v127
	v_mad_u32_u24 v106, v0, s4, 0
	v_lshlrev_b32_e32 v0, 1, v0
	s_mul_i32 s4, s77, 0x2100
	v_lshl_add_u64 v[32:33], s[40:41], 0, v[0:1]
	v_and_b32_e32 v0, 31, v126
	s_add_i32 s4, s4, 0
	v_lshl_add_u32 v107, v0, 4, s4
	v_lshlrev_b32_e32 v0, 4, v73
	v_lshl_add_u64 v[0:1], s[34:35], 0, v[0:1]
	s_mov_b64 s[4:5], 0xc000800
	v_lshrrev_b32_e32 v104, 5, v73
	v_and_b32_e32 v105, 0xf8, v72
	s_lshl_b32 s3, s77, 4
	v_lshl_add_u64 v[34:35], v[0:1], 0, s[4:5]
	v_mov_b32_e32 v108, 0x4800
	s_mov_b32 s48, 0x3a800000
	s_mov_b32 s50, 0x358637bd
	s_mov_b32 s19, 0x800000
	s_mov_b64 s[52:53], 0x12000
	s_mov_b32 s25, s99

.LBB0_352:
	s_waitcnt vmcnt(0)
	v_mov_b32_e32 v0, v164
	s_mov_b32 s4, 11
	v_mov_b32_e32 v8, v164
	s_waitcnt lgkmcnt(0)
	s_barrier
	s_andn2_b64 vcc, exec, s[42:43]
	v_readfirstlane_b32 s10, v8
	s_cbranch_vccnz .LBB0_379
	v_lshlrev_b32_e32 v0, 4, v8
	v_add_u32_e32 v1, 0x2000, v0
	v_ashrrev_i32_e32 v2, 31, v1
	v_lshrrev_b32_e32 v2, 22, v2
	v_add_u32_e32 v2, v1, v2
	v_ashrrev_i32_e32 v9, 10, v2
	v_mul_i32_i24_e32 v2, 0x400, v9
	v_sub_u32_e32 v1, v1, v2
	v_lshrrev_b32_e32 v2, 4, v1
	v_bitop3_b32 v1, v2, v1, 32 bitop3:0x6c
	v_ashrrev_i32_e32 v2, 31, v1
	v_lshrrev_b32_e32 v2, 26, v2
	v_add_u32_e32 v2, v1, v2
	v_lshlrev_b32_e32 v3, 3, v9
	v_ashrrev_i32_e32 v10, 6, v2
	v_and_b32_e32 v3, -16, v3
	v_add_u32_e32 v3, v10, v3
	v_and_b32_e32 v4, 3, v10
	s_mov_b32 s6, 0xffffe0
	v_lshrrev_b32_e32 v5, 2, v3
	v_lshlrev_b32_e32 v6, 1, v3
	v_and_b32_e32 v2, 0xc0, v2
	v_and_or_b32 v4, v3, s6, v4
	v_and_b32_e32 v5, 4, v5
	v_and_b32_e32 v6, 24, v6
	v_sub_u32_e32 v1, v1, v2
	v_mov_b32_e32 v2, 1
	v_or3_b32 v4, v4, v5, v6
	v_lshlrev_b32_e32 v5, 5, v9
	v_ashrrev_i16_sdwa v1, v2, sext(v1) dst_sel:DWORD dst_unused:UNUSED_PAD src0_sel:DWORD src1_sel:BYTE_0
	v_and_b32_e32 v5, 32, v5
	v_bfe_i32 v11, v1, 0, 16
	v_add_lshl_u32 v1, v5, v11, 1
	v_lshl_add_u32 v132, v4, 8, v1
	v_lshl_add_u32 v134, v3, 8, v1
	v_bfe_i32 v1, v8, 27, 1
	v_lshrrev_b32_e32 v1, 22, v1
	v_add_u32_e32 v1, v0, v1
	v_and_b32_e32 v1, 0xfffffc00, v1
	v_sub_u32_e32 v0, v0, v1
	v_lshrrev_b32_e32 v1, 4, v0
	v_ashrrev_i32_e32 v3, 31, v8
	v_bitop3_b32 v0, v1, v0, 32 bitop3:0x6c
	v_lshrrev_b32_e32 v3, 26, v3
	v_ashrrev_i32_e32 v1, 31, v0
	v_add_u32_e32 v3, v8, v3
	s_add_u32 s3, s34, 0x9600000
	v_lshrrev_b32_e32 v1, 26, v1
	v_ashrrev_i32_e32 v13, 6, v3
	s_addc_u32 s19, s35, 0
	s_ashr_i32 s5, s4, 31
	v_add_u32_e32 v1, v0, v1
	v_lshlrev_b32_e32 v3, 3, v13
	s_lshl_b64 s[4:5], s[4:5], 3
	v_ashrrev_i32_e32 v12, 6, v1
	v_and_b32_e32 v3, -16, v3
	s_add_u32 s4, s0, s4
	v_add_u32_e32 v3, v12, v3
	v_and_b32_e32 v4, 3, v12
	s_addc_u32 s5, s1, s5
	s_ashr_i32 s11, s10, 6
	v_and_or_b32 v4, v3, s6, v4
	s_lshl_b32 s6, s99, 15
	s_ashr_i32 s42, s10, 8
	s_lshl_b32 s25, s11, 10
	s_ashr_i32 s8, s99, 2
	s_and_b32 s6, s6, 0x10000
	s_add_u32 s48, s3, s6
	s_addc_u32 s49, s19, 0
	s_lshl_b32 s6, s99, 8
	s_ashr_i32 s9, s8, 31
	s_and_b32 s76, s6, 0x300
	v_lshrrev_b32_e32 v5, 2, v3
	v_lshlrev_b32_e32 v6, 1, v3
	v_and_b32_e32 v1, 0xc0, v1
	s_lshl_b32 s12, s76, 8
	s_lshl_b64 s[6:7], s[8:9], 18
	v_and_b32_e32 v5, 4, v5
	v_and_b32_e32 v6, 24, v6
	v_sub_u32_e32 v0, v0, v1
	s_add_u32 s6, s40, s6
	v_or3_b32 v4, v4, v5, v6
	v_lshlrev_b32_e32 v5, 5, v13
	v_ashrrev_i16_sdwa v0, v2, sext(v0) dst_sel:DWORD dst_unused:UNUSED_PAD src0_sel:DWORD src1_sel:BYTE_0
	s_addc_u32 s7, s41, s7
	v_and_b32_e32 v5, 32, v5
	v_bfe_i32 v14, v0, 0, 16
	s_add_u32 s50, s6, s12
	v_add_lshl_u32 v0, v5, v14, 1
	s_addc_u32 s51, s7, 0
	s_add_i32 s29, s25, 0
	v_lshl_add_u32 v136, v4, 8, v0
	s_add_i32 m0, s29, 0x10000
	v_lshl_add_u32 v138, v3, 8, v0
	global_load_lds_dwordx4 v136, s[50:51]
	s_add_i32 m0, s29, 0x12000
	s_add_u32 s6, s50, 0x8000
	global_load_lds_dwordx4 v132, s[50:51]
	s_addc_u32 s7, s51, 0
	s_add_i32 m0, s29, 0x14000
	s_add_i32 s54, s29, 0x2000
	global_load_lds_dwordx4 v136, s[6:7]
	s_add_i32 m0, s29, 0x16000
	s_load_dwordx2 s[4:5], s[4:5], 0x0
	global_load_lds_dwordx4 v132, s[6:7]
	s_mov_b32 m0, s29
	s_add_u32 s6, s48, 0x8000
	global_load_lds_dwordx4 v138, s[48:49]
	s_mov_b32 m0, s54
	s_addc_u32 s7, s49, 0
	s_add_i32 s55, s29, 0x4000
	global_load_lds_dwordx4 v134, s[48:49]
	s_mov_b32 m0, s55
	s_add_i32 s56, s29, 0x6000
	global_load_lds_dwordx4 v138, s[6:7]
	s_mov_b32 m0, s56
	v_mov_b32_e32 v137, 0
	global_load_lds_dwordx4 v134, s[6:7]
	v_mov_b32_e32 v133, v137
	v_mov_b32_e32 v139, v137
	v_mov_b32_e32 v135, v137
	s_cmp_eq_u32 s42, 1
	s_mov_b32 s57, 0
	v_lshl_add_u64 v[6:7], s[50:51], 0, v[136:137]
	v_lshl_add_u64 v[4:5], s[50:51], 0, v[132:133]
	v_lshl_add_u64 v[0:1], s[48:49], 0, v[138:139]
	s_cselect_b64 s[6:7], -1, 0
	s_cmp_lg_u32 s42, 1
	v_lshl_add_u64 v[2:3], s[48:49], 0, v[134:135]
	s_cbranch_scc1 .LBB0_355
	s_barrier
.LBB0_355:
	s_lshl_b32 s75, s8, 7
	s_lshl_b32 s8, s11, 5
	s_and_b32 s59, s8, 0x60
	s_mov_b64 s[8:9], 0x80
	s_add_i32 m0, s29, 0x18000
	v_lshl_add_u64 v[6:7], v[6:7], 0, s[8:9]
	s_and_b32 s79, s99, 1
	s_lshl_b32 s58, s42, 6
	s_lshl_b32 s12, s42, 13
	s_lshl_b32 s11, s59, 7
	s_waitcnt vmcnt(2)
	s_barrier
	global_load_lds_dwordx4 v[6:7], off
	v_lshl_add_u64 v[4:5], v[4:5], 0, s[8:9]
	s_add_i32 m0, s29, 0x1a000
	s_add_i32 s60, s29, 0x8000
	s_add_i32 s61, s29, 0xa000
	global_load_lds_dwordx4 v[4:5], off
	v_lshl_add_u64 v[0:1], v[0:1], 0, s[8:9]
	s_mov_b32 m0, s60
	s_add_u32 s42, s50, 0x8080
	global_load_lds_dwordx4 v[0:1], off
	v_lshl_add_u64 v[0:1], v[2:3], 0, s[8:9]
	s_mov_b32 m0, s61
	s_addc_u32 s43, s51, 0
	global_load_lds_dwordx4 v[0:1], off
	s_add_i32 m0, s29, 0x1c000
	v_lshl_add_u64 v[0:1], s[42:43], 0, v[136:137]
	global_load_lds_dwordx4 v[0:1], off
	v_lshl_add_u64 v[0:1], s[42:43], 0, v[132:133]
	s_add_i32 m0, s29, 0x1e000
	v_bfe_u32 v149, v8, 4, 2
	global_load_lds_dwordx4 v[0:1], off
	v_and_b32_e32 v148, 15, v8
	v_lshlrev_b32_e32 v0, 4, v149
	v_lshlrev_b32_e32 v1, 2, v8
	v_lshl_or_b32 v0, v148, 6, v0
	v_and_b32_e32 v1, 32, v1
	v_bitop3_b32 v2, v0, s12, v1 bitop3:0xde
	v_bitop3_b32 v0, v0, s11, v1 bitop3:0xde
	v_lshlrev_b32_e32 v1, 11, v9
	v_and_b32_e32 v1, 0xfffff000, v1
	v_lshl_add_u32 v1, v10, 8, v1
	v_and_b32_e32 v3, 1, v9
	v_lshl_or_b32 v1, v3, 6, v1
	v_lshl_add_u32 v140, v11, 1, v1
	v_lshlrev_b32_e32 v1, 11, v13
	s_cmpk_lt_u32 s10, 0x100
	v_and_b32_e32 v1, 0xfffff000, v1
	s_waitcnt vmcnt(6)
	s_cselect_b64 s[10:11], -1, 0
	v_lshl_add_u32 v1, v12, 8, v1
	v_and_b32_e32 v3, 1, v13
	s_add_i32 s67, 0, 0x14000
	s_add_i32 s65, 0, 0x10000
	s_add_i32 s70, 0, 0x18000
	v_lshl_or_b32 v1, v3, 6, v1
	v_add_u32_e32 v150, s67, v0
	v_add_u32_e32 v152, s65, v0
	s_add_i32 s65, s65, s25
	s_add_i32 s67, s67, s25
	v_add_u32_e32 v153, s70, v0
	s_add_i32 s69, 0, 0x1c000
	s_add_i32 s70, s70, s25
	v_mov_b32_e32 v141, v137
	v_lshl_add_u32 v142, v14, 1, v1
	v_mov_b32_e32 v143, v137
	v_add_u32_e32 v151, 0, v2
	s_movk_i32 s62, 0x4800
	s_add_i32 s63, s29, 0xc000
	s_add_i32 s64, s29, 0xe000
	s_add_i32 s66, s65, 0x2000
	s_add_i32 s68, s67, 0x2000
	v_add_u32_e32 v154, s69, v0
	s_add_i32 s71, s70, 0x2000
	s_mov_b64 s[44:45], s[50:51]
	s_mov_b64 s[42:43], s[48:49]
	s_barrier
	s_branch .LBB0_358

.LBB0_358:
	s_add_i32 s57, s57, 1
	s_mul_i32 s52, s57, s26
	s_add_i32 s52, s52, s99
	s_cmpk_lt_i32 s52, 0x100
	s_cselect_b64 s[46:47], -1, 0
	s_cmpk_gt_i32 s52, 0xff
	s_cbranch_scc1 .LBB0_360
	s_lshl_b32 s12, s52, 15
	s_ashr_i32 s80, s52, 2
	s_and_b32 s72, s52, 1
	s_and_b32 s12, s12, 0x10000
	s_add_u32 s42, s3, s12
	s_addc_u32 s43, s19, 0
	s_lshl_b32 s12, s52, 8
	s_ashr_i32 s81, s80, 31
	s_and_b32 s73, s12, 0x300
	s_lshl_b32 s12, s73, 8
	s_lshl_b64 s[44:45], s[80:81], 18
	s_add_u32 s13, s40, s44
	s_addc_u32 s45, s41, s45
	s_add_u32 s44, s13, s12
	s_addc_u32 s45, s45, 0
	s_lshl_b32 s74, s80, 7
